# prep compression MLP: 8-step serial cross-wave LDS reduction replaced by per-wave partial tiles + one parallel sum (same summation order)
# speedup vs baseline: 1.0425x; 1.0072x over previous
.LBB0_616:
	v_add_u32_e32 v199, s58, v166
	v_add_u32_e32 v200, 64, v199
	v_add_u32_e32 v201, 128, v199
	v_add_u32_e32 v202, 192, v199
	s_nop 7
	s_nop 7
	ds_write2st64_b32 v199, v30, v31 offset1:4
	ds_write2st64_b32 v199, v32, v33 offset0:8 offset1:12
	ds_write2st64_b32 v200, v26, v27 offset1:4
	ds_write2st64_b32 v200, v28, v29 offset0:8 offset1:12
	ds_write2st64_b32 v201, v22, v23 offset1:4
	ds_write2st64_b32 v201, v24, v25 offset0:8 offset1:12
	ds_write2st64_b32 v202, v18, v19 offset1:4
	ds_write2st64_b32 v202, v20, v21 offset0:8 offset1:12
	ds_write2st64_b32 v199, v14, v15 offset0:1 offset1:5
	ds_write2st64_b32 v199, v16, v17 offset0:9 offset1:13
	ds_write2st64_b32 v200, v10, v11 offset0:1 offset1:5
	ds_write2st64_b32 v200, v12, v13 offset0:9 offset1:13
	ds_write2st64_b32 v201, v6, v7 offset0:1 offset1:5
	ds_write2st64_b32 v201, v8, v9 offset0:9 offset1:13
	ds_write2st64_b32 v202, v2, v3 offset0:1 offset1:5
	ds_write2st64_b32 v202, v4, v5 offset0:9 offset1:13
	ds_write2st64_b32 v199, v34, v35 offset0:2 offset1:6
	ds_write2st64_b32 v199, v36, v37 offset0:10 offset1:14
	ds_write2st64_b32 v200, v38, v39 offset0:2 offset1:6
	ds_write2st64_b32 v200, v40, v41 offset0:10 offset1:14
	ds_write2st64_b32 v201, v42, v43 offset0:2 offset1:6
	ds_write2st64_b32 v201, v44, v45 offset0:10 offset1:14
	ds_write2st64_b32 v202, v46, v47 offset0:2 offset1:6
	ds_write2st64_b32 v202, v48, v49 offset0:10 offset1:14
	ds_write2st64_b32 v199, v50, v51 offset0:3 offset1:7
	ds_write2st64_b32 v199, v52, v53 offset0:11 offset1:15
	ds_write2st64_b32 v200, v54, v55 offset0:3 offset1:7
	ds_write2st64_b32 v200, v56, v57 offset0:11 offset1:15
	ds_write2st64_b32 v201, v58, v59 offset0:3 offset1:7
	ds_write2st64_b32 v201, v60, v61 offset0:11 offset1:15
	ds_write2st64_b32 v202, v62, v63 offset0:3 offset1:7
	ds_write2st64_b32 v202, v64, v65 offset0:11 offset1:15
	s_waitcnt lgkmcnt(0)
	s_barrier
	v_lshlrev_b32_e32 v203, 4, v180
	v_add_u32_e32 v204, 0x10000, v203
	ds_read_b128 v[2:5], v203
	ds_read_b128 v[6:9], v203 offset:8192
	ds_read_b128 v[10:13], v203 offset:16384
	ds_read_b128 v[14:17], v203 offset:24576
	ds_read_b128 v[18:21], v203 offset:32768
	ds_read_b128 v[22:25], v203 offset:40960
	ds_read_b128 v[26:29], v203 offset:49152
	ds_read_b128 v[30:33], v203 offset:57344
	ds_read_b128 v[34:37], v204
	ds_read_b128 v[38:41], v204 offset:8192
	ds_read_b128 v[42:45], v204 offset:16384
	ds_read_b128 v[46:49], v204 offset:24576
	ds_read_b128 v[50:53], v204 offset:32768
	ds_read_b128 v[54:57], v204 offset:40960
	ds_read_b128 v[58:61], v204 offset:49152
	ds_read_b128 v[62:65], v204 offset:57344
	s_waitcnt lgkmcnt(12)
	v_add_f32_e32 v2, v2, v10
	v_add_f32_e32 v3, v3, v11
	v_add_f32_e32 v4, v4, v12
	v_add_f32_e32 v5, v5, v13
	v_add_f32_e32 v6, v6, v14
	v_add_f32_e32 v7, v7, v15
	v_add_f32_e32 v8, v8, v16
	v_add_f32_e32 v9, v9, v17
	s_waitcnt lgkmcnt(10)
	v_add_f32_e32 v2, v2, v18
	v_add_f32_e32 v3, v3, v19
	v_add_f32_e32 v4, v4, v20
	v_add_f32_e32 v5, v5, v21
	v_add_f32_e32 v6, v6, v22
	v_add_f32_e32 v7, v7, v23
	v_add_f32_e32 v8, v8, v24
	v_add_f32_e32 v9, v9, v25
	s_waitcnt lgkmcnt(8)
	v_add_f32_e32 v2, v2, v26
	v_add_f32_e32 v3, v3, v27
	v_add_f32_e32 v4, v4, v28
	v_add_f32_e32 v5, v5, v29
	v_add_f32_e32 v6, v6, v30
	v_add_f32_e32 v7, v7, v31
	v_add_f32_e32 v8, v8, v32
	v_add_f32_e32 v9, v9, v33
	s_waitcnt lgkmcnt(6)
	v_add_f32_e32 v2, v2, v34
	v_add_f32_e32 v3, v3, v35
	v_add_f32_e32 v4, v4, v36
	v_add_f32_e32 v5, v5, v37
	v_add_f32_e32 v6, v6, v38
	v_add_f32_e32 v7, v7, v39
	v_add_f32_e32 v8, v8, v40
	v_add_f32_e32 v9, v9, v41
	s_waitcnt lgkmcnt(4)
	v_add_f32_e32 v2, v2, v42
	v_add_f32_e32 v3, v3, v43
	v_add_f32_e32 v4, v4, v44
	v_add_f32_e32 v5, v5, v45
	v_add_f32_e32 v6, v6, v46
	v_add_f32_e32 v7, v7, v47
	v_add_f32_e32 v8, v8, v48
	v_add_f32_e32 v9, v9, v49
	s_waitcnt lgkmcnt(2)
	v_add_f32_e32 v2, v2, v50
	v_add_f32_e32 v3, v3, v51
	v_add_f32_e32 v4, v4, v52
	v_add_f32_e32 v5, v5, v53
	v_add_f32_e32 v6, v6, v54
	v_add_f32_e32 v7, v7, v55
	v_add_f32_e32 v8, v8, v56
	v_add_f32_e32 v9, v9, v57
	s_waitcnt lgkmcnt(0)
	v_add_f32_e32 v2, v2, v58
	v_add_f32_e32 v3, v3, v59
	v_add_f32_e32 v4, v4, v60
	v_add_f32_e32 v5, v5, v61
	v_add_f32_e32 v6, v6, v62
	v_add_f32_e32 v7, v7, v63
	v_add_f32_e32 v8, v8, v64
	v_add_f32_e32 v9, v9, v65
	ds_write_b128 v203, v[2:5]
	ds_write_b128 v203, v[6:9] offset:8192
	s_waitcnt lgkmcnt(0)
	s_barrier
